# mla_up K step: all 8 next-step loads issued back to back, waits and register copies moved to the LDS write that consumes them
# baseline (speedup 1.0000x reference)
.LBB0_454:
	v_lshl_add_u64 v[64:65], v[134:135], 0, s[0:1]
	v_add_co_u32_e32 v64, vcc, 0x60b1000, v64
	v_lshl_add_u64 v[66:67], v[136:137], 0, s[0:1]
	s_nop 0
	v_addc_co_u32_e32 v65, vcc, 0, v65, vcc
	v_add_co_u32_e32 v68, vcc, 0x60b1000, v66
	s_waitcnt vmcnt(3)
	v_lshl_add_u64 v[72:73], v[138:139], 0, s[0:1]
	v_addc_co_u32_e32 v69, vcc, 0, v67, vcc
	v_add_co_u32_e32 v72, vcc, 0x60b1000, v72
	v_lshl_add_u64 v[74:75], v[140:141], 0, s[0:1]
	s_nop 0
	v_addc_co_u32_e32 v73, vcc, 0, v73, vcc
	v_add_co_u32_e32 v74, vcc, 0x60b1000, v74
	s_waitcnt vmcnt(1)
	v_lshl_add_u64 v[88:89], v[142:143], 0, s[0:1]
	v_addc_co_u32_e32 v75, vcc, 0, v75, vcc
	global_load_dwordx4 v[64:67], v[64:65], off offset:128
	s_nop 0
	global_load_dwordx4 v[68:71], v[68:69], off offset:128
	s_nop 0
	global_load_dwordx4 v[80:83], v[72:73], off offset:128
	global_load_dwordx4 v[84:87], v[74:75], off offset:128
	v_add_co_u32_e32 v72, vcc, 0x1d31000, v88
	v_addc_co_u32_e32 v73, vcc, 0, v89, vcc
	v_add_co_u32_e32 v76, vcc, 0x1d35000, v88
	s_nop 0
	v_addc_co_u32_e32 v77, vcc, 0, v89, vcc
	v_add_co_u32_e32 v90, vcc, 0x1d39000, v88
	global_load_dwordx4 v[72:75], v[72:73], off offset:128
	s_nop 0
	global_load_dwordx4 v[76:79], v[76:77], off offset:128
	v_addc_co_u32_e32 v91, vcc, 0, v89, vcc
	v_add_co_u32_e32 v92, vcc, 0x1d3d000, v88
	s_nop 0
	v_addc_co_u32_e32 v93, vcc, 0, v89, vcc
	global_load_dwordx4 v[88:91], v[90:91], off offset:128
	s_nop 0
	global_load_dwordx4 v[92:95], v[92:93], off offset:128
	s_branch .LBB0_456

.LBB0_456:
	s_add_i32 s29, s28, 1
	s_bitcmp1_b32 s28, 0
	s_cselect_b32 s28, 0x9000, 0
	v_add_u32_e32 v236, s28, v194
	v_lshlrev_b32_e32 v237, 1, v129
	v_add3_u32 v238, v236, v164, v237
	ds_read_b128 v[224:227], v238
	v_add3_u32 v236, v236, v165, v237
	ds_read_b128 v[228:231], v236 offset:18432
	ds_read_b128 v[232:235], v236 offset:23040
	s_andn2_b64 vcc, exec, s[10:11]
	s_waitcnt lgkmcnt(1)
	v_mfma_f32_32x32x16_bf16 v[0:15], v[224:227], v[228:231], v[0:15]
	s_waitcnt lgkmcnt(0)
	v_mfma_f32_32x32x16_bf16 v[16:31], v[224:227], v[232:235], v[16:31]
	ds_read_b128 v[224:227], v238 offset:4608
	s_waitcnt lgkmcnt(0)
	v_mfma_f32_32x32x16_bf16 v[32:47], v[224:227], v[228:231], v[32:47]
	v_mfma_f32_32x32x16_bf16 v[48:63], v[224:227], v[232:235], v[48:63]
	ds_read_b128 v[224:227], v238 offset:32
	ds_read_b128 v[228:231], v236 offset:18464
	ds_read_b128 v[232:235], v236 offset:23072
	s_waitcnt lgkmcnt(1)
	v_mfma_f32_32x32x16_bf16 v[0:15], v[224:227], v[228:231], v[0:15]
	s_waitcnt lgkmcnt(0)
	v_mfma_f32_32x32x16_bf16 v[16:31], v[224:227], v[232:235], v[16:31]
	ds_read_b128 v[224:227], v238 offset:4640
	s_waitcnt lgkmcnt(0)
	v_mfma_f32_32x32x16_bf16 v[32:47], v[224:227], v[228:231], v[32:47]
	v_mfma_f32_32x32x16_bf16 v[48:63], v[224:227], v[232:235], v[48:63]
	ds_read_b128 v[224:227], v238 offset:64
	ds_read_b128 v[228:231], v236 offset:18496
	ds_read_b128 v[232:235], v236 offset:23104
	s_waitcnt lgkmcnt(1)
	v_mfma_f32_32x32x16_bf16 v[0:15], v[224:227], v[228:231], v[0:15]
	s_waitcnt lgkmcnt(0)
	v_mfma_f32_32x32x16_bf16 v[16:31], v[224:227], v[232:235], v[16:31]
	ds_read_b128 v[224:227], v238 offset:4672
	s_waitcnt lgkmcnt(0)
	v_mfma_f32_32x32x16_bf16 v[32:47], v[224:227], v[228:231], v[32:47]
	v_mfma_f32_32x32x16_bf16 v[48:63], v[224:227], v[232:235], v[48:63]
	ds_read_b128 v[224:227], v238 offset:96
	ds_read_b128 v[228:231], v236 offset:18528
	ds_read_b128 v[232:235], v236 offset:23136
	s_waitcnt lgkmcnt(1)
	v_mfma_f32_32x32x16_bf16 v[0:15], v[224:227], v[228:231], v[0:15]
	s_waitcnt lgkmcnt(0)
	v_mfma_f32_32x32x16_bf16 v[16:31], v[224:227], v[232:235], v[16:31]
	ds_read_b128 v[224:227], v238 offset:4704
	s_waitcnt lgkmcnt(0)
	v_mfma_f32_32x32x16_bf16 v[32:47], v[224:227], v[228:231], v[32:47]
	v_mfma_f32_32x32x16_bf16 v[48:63], v[224:227], v[232:235], v[48:63]
	s_cbranch_vccnz .LBB0_458
	s_waitcnt vmcnt(7)
	v_mov_b32_e32 v157, v67
	v_mov_b32_e32 v161, v66
	v_mov_b32_e32 v163, v65
	s_waitcnt vmcnt(6)
	v_mov_b32_e32 v156, v71
	v_mov_b32_e32 v160, v70
	v_mov_b32_e32 v162, v69
	v_mov_b32_e32 v146, v71
	s_waitcnt vmcnt(5)
	v_mov_b32_e32 v153, v83
	v_mov_b32_e32 v155, v82
	v_mov_b32_e32 v159, v81
	v_mov_b32_e32 v145, v83
	v_mov_b32_e32 v149, v81
	s_waitcnt vmcnt(4)
	v_mov_b32_e32 v152, v87
	v_mov_b32_e32 v154, v86
	v_mov_b32_e32 v158, v85
	v_mov_b32_e32 v144, v87
	v_mov_b32_e32 v87, v82
	v_mov_b32_e32 v148, v85
	v_mov_b32_e32 v147, v67
	v_mov_b32_e32 v71, v66
	v_mov_b32_e32 v150, v69
	v_mov_b32_e32 v151, v65
	s_bitcmp1_b32 s29, 0
	s_cselect_b32 s10, 0x9000, 0
	v_add_u32_e32 v69, s10, v123
	v_mov_b32_e32 v81, v159
	v_mov_b32_e32 v82, v155
	v_mov_b32_e32 v83, v145
	v_mov_b32_e32 v65, v163
	v_mov_b32_e32 v66, v161
	v_mov_b32_e32 v67, v147
	v_mov_b32_e32 v224, v68
	v_mov_b32_e32 v225, v162
	v_mov_b32_e32 v226, v160
	v_mov_b32_e32 v227, v146
	ds_write_b128 v69, v[80:83] offset:9216
	v_and_b32_e32 v83, 0xffff0000, v64
	v_and_b32_e32 v82, 0xffff0000, v68
	ds_write_b128 v69, v[64:67]
	ds_write_b128 v69, v[224:227] offset:4608
	v_mov_b32_e32 v224, v84
	v_mov_b32_e32 v225, v158
	v_mov_b32_e32 v226, v154
	v_mov_b32_e32 v227, v144
	v_lshlrev_b32_e32 v67, 16, v64
	v_lshlrev_b32_e32 v66, 16, v68
	v_pk_mul_f32 v[82:83], v[82:83], v[82:83]
	ds_write_b128 v69, v[224:227] offset:13824
	s_waitcnt vmcnt(3)
	ds_write_b128 v69, v[72:75] offset:18432
	s_waitcnt vmcnt(2)
	ds_write_b128 v69, v[76:79] offset:23040
	s_waitcnt vmcnt(1)
	ds_write_b128 v69, v[88:91] offset:27648
	s_waitcnt vmcnt(0)
	ds_write_b128 v69, v[92:95] offset:32256
	v_lshlrev_b32_e32 v225, 16, v163
	v_lshlrev_b32_e32 v224, 16, v162
	v_pk_fma_f32 v[66:67], v[66:67], v[66:67], v[82:83]
	v_and_b32_e32 v163, 0xffff0000, v163
	v_and_b32_e32 v162, 0xffff0000, v162
	v_pk_fma_f32 v[66:67], v[224:225], v[224:225], v[66:67]
	v_lshlrev_b32_e32 v227, 16, v161
	v_lshlrev_b32_e32 v226, 16, v160
	v_pk_fma_f32 v[66:67], v[162:163], v[162:163], v[66:67]
	v_and_b32_e32 v161, 0xffff0000, v161
	v_and_b32_e32 v160, 0xffff0000, v160
	v_pk_fma_f32 v[66:67], v[226:227], v[226:227], v[66:67]
	v_lshlrev_b32_e32 v229, 16, v157
	v_lshlrev_b32_e32 v228, 16, v156
	v_pk_fma_f32 v[66:67], v[160:161], v[160:161], v[66:67]
	v_and_b32_e32 v157, 0xffff0000, v157
	v_and_b32_e32 v156, 0xffff0000, v156
	v_pk_fma_f32 v[66:67], v[228:229], v[228:229], v[66:67]
	v_and_b32_e32 v83, 0xffff0000, v80
	v_pk_fma_f32 v[66:67], v[156:157], v[156:157], v[66:67]
	v_and_b32_e32 v82, 0xffff0000, v84
	v_pk_add_f32 v[126:127], v[126:127], v[66:67]
	v_lshlrev_b32_e32 v67, 16, v80
	v_lshlrev_b32_e32 v66, 16, v84
	v_pk_mul_f32 v[82:83], v[82:83], v[82:83]
	v_lshlrev_b32_e32 v157, 16, v159
	v_lshlrev_b32_e32 v156, 16, v158
	v_pk_fma_f32 v[66:67], v[66:67], v[66:67], v[82:83]
	v_and_b32_e32 v159, 0xffff0000, v159
	v_and_b32_e32 v158, 0xffff0000, v158
	v_pk_fma_f32 v[66:67], v[156:157], v[156:157], v[66:67]
	v_lshlrev_b32_e32 v161, 16, v155
	v_lshlrev_b32_e32 v160, 16, v154
	v_pk_fma_f32 v[66:67], v[158:159], v[158:159], v[66:67]
	v_and_b32_e32 v155, 0xffff0000, v155
	v_and_b32_e32 v154, 0xffff0000, v154
	v_pk_fma_f32 v[66:67], v[160:161], v[160:161], v[66:67]
	v_lshlrev_b32_e32 v163, 16, v153
	v_lshlrev_b32_e32 v162, 16, v152
	v_pk_fma_f32 v[66:67], v[154:155], v[154:155], v[66:67]
	v_and_b32_e32 v153, 0xffff0000, v153
	v_and_b32_e32 v152, 0xffff0000, v152
	v_pk_fma_f32 v[66:67], v[162:163], v[162:163], v[66:67]
	s_nop 0
	v_pk_fma_f32 v[66:67], v[152:153], v[152:153], v[66:67]
	s_nop 0
	v_pk_add_f32 v[124:125], v[124:125], v[66:67]

.LBB0_473:
	v_lshl_add_u64 v[72:73], v[134:135], 0, s[0:1]
	v_add_co_u32_e32 v64, vcc, 0x5331000, v72
	s_waitcnt vmcnt(1)
	v_lshl_add_u64 v[80:81], v[136:137], 0, s[0:1]
	v_addc_co_u32_e32 v65, vcc, 0, v73, vcc
	v_add_co_u32_e32 v68, vcc, 0x5337000, v72
	s_nop 1
	v_addc_co_u32_e32 v69, vcc, 0, v73, vcc
	v_add_co_u32_e32 v74, vcc, 0x533d000, v72
	global_load_dwordx4 v[64:67], v[64:65], off offset:128
	s_nop 0
	global_load_dwordx4 v[68:71], v[68:69], off offset:128
	v_addc_co_u32_e32 v75, vcc, 0, v73, vcc
	v_add_co_u32_e32 v76, vcc, 0x5343000, v72
	v_addc_co_u32_e32 v77, vcc, 0, v73, vcc
	global_load_dwordx4 v[72:75], v[74:75], off offset:128
	s_nop 0
	global_load_dwordx4 v[92:95], v[76:77], off offset:128
	v_add_co_u32_e32 v76, vcc, 0x1c71000, v80
	s_nop 0
	v_addc_co_u32_e32 v77, vcc, 0, v81, vcc
	v_add_co_u32_e32 v82, vcc, 0x1c77000, v80
	s_nop 0
	v_addc_co_u32_e32 v83, vcc, 0, v81, vcc
	global_load_dwordx4 v[76:79], v[76:77], off offset:128
	s_nop 0
	global_load_dwordx4 v[88:91], v[82:83], off offset:128
	v_add_co_u32_e32 v82, vcc, 0x1c7d000, v80
	v_addc_co_u32_e32 v83, vcc, 0, v81, vcc
	v_add_co_u32_e32 v84, vcc, 0x1c83000, v80
	s_nop 0
	v_addc_co_u32_e32 v85, vcc, 0, v81, vcc
	global_load_dwordx4 v[80:83], v[82:83], off offset:128
	s_nop 0
	global_load_dwordx4 v[84:87], v[84:85], off offset:128
	s_branch .LBB0_475

.LBB0_475:
	s_add_i32 s29, s28, 1
	s_bitcmp1_b32 s28, 0
	s_cselect_b32 s28, 0x9000, 0
	v_add_u32_e32 v236, s28, v194
	v_lshlrev_b32_e32 v237, 1, v129
	v_add3_u32 v238, v236, v164, v237
	ds_read_b128 v[158:161], v238
	v_add3_u32 v236, v236, v165, v237
	ds_read_b128 v[222:225], v236 offset:18432
	ds_read_b128 v[226:229], v236 offset:23040
	s_andn2_b64 vcc, exec, s[10:11]
	s_waitcnt lgkmcnt(1)
	v_mfma_f32_32x32x16_bf16 v[0:15], v[158:161], v[222:225], v[0:15]
	s_waitcnt lgkmcnt(0)
	v_mfma_f32_32x32x16_bf16 v[16:31], v[158:161], v[226:229], v[16:31]
	ds_read_b128 v[158:161], v238 offset:4608
	s_waitcnt lgkmcnt(0)
	v_mfma_f32_32x32x16_bf16 v[32:47], v[158:161], v[222:225], v[32:47]
	v_mfma_f32_32x32x16_bf16 v[48:63], v[158:161], v[226:229], v[48:63]
	ds_read_b128 v[158:161], v238 offset:32
	ds_read_b128 v[222:225], v236 offset:18464
	ds_read_b128 v[226:229], v236 offset:23072
	s_waitcnt lgkmcnt(1)
	v_mfma_f32_32x32x16_bf16 v[0:15], v[158:161], v[222:225], v[0:15]
	s_waitcnt lgkmcnt(0)
	v_mfma_f32_32x32x16_bf16 v[16:31], v[158:161], v[226:229], v[16:31]
	ds_read_b128 v[158:161], v238 offset:4640
	s_waitcnt lgkmcnt(0)
	v_mfma_f32_32x32x16_bf16 v[32:47], v[158:161], v[222:225], v[32:47]
	v_mfma_f32_32x32x16_bf16 v[48:63], v[158:161], v[226:229], v[48:63]
	ds_read_b128 v[158:161], v238 offset:64
	ds_read_b128 v[222:225], v236 offset:18496
	ds_read_b128 v[226:229], v236 offset:23104
	s_waitcnt lgkmcnt(1)
	v_mfma_f32_32x32x16_bf16 v[0:15], v[158:161], v[222:225], v[0:15]
	s_waitcnt lgkmcnt(0)
	v_mfma_f32_32x32x16_bf16 v[16:31], v[158:161], v[226:229], v[16:31]
	ds_read_b128 v[158:161], v238 offset:4672
	s_waitcnt lgkmcnt(0)
	v_mfma_f32_32x32x16_bf16 v[32:47], v[158:161], v[222:225], v[32:47]
	v_mfma_f32_32x32x16_bf16 v[48:63], v[158:161], v[226:229], v[48:63]
	ds_read_b128 v[158:161], v238 offset:96
	ds_read_b128 v[222:225], v236 offset:18528
	ds_read_b128 v[226:229], v236 offset:23136
	s_waitcnt lgkmcnt(1)
	v_mfma_f32_32x32x16_bf16 v[0:15], v[158:161], v[222:225], v[0:15]
	s_waitcnt lgkmcnt(0)
	v_mfma_f32_32x32x16_bf16 v[16:31], v[158:161], v[226:229], v[16:31]
	ds_read_b128 v[158:161], v238 offset:4704
	s_waitcnt lgkmcnt(0)
	v_mfma_f32_32x32x16_bf16 v[32:47], v[158:161], v[222:225], v[32:47]
	v_mfma_f32_32x32x16_bf16 v[48:63], v[158:161], v[226:229], v[48:63]
	s_cbranch_vccnz .LBB0_477
	s_waitcnt vmcnt(7)
	v_mov_b32_e32 v151, v67
	v_mov_b32_e32 v155, v66
	v_mov_b32_e32 v157, v65
	s_waitcnt vmcnt(6)
	v_mov_b32_e32 v150, v71
	v_mov_b32_e32 v154, v70
	v_mov_b32_e32 v156, v69
	v_mov_b32_e32 v140, v71
	v_mov_b32_e32 v141, v67
	v_mov_b32_e32 v71, v66
	v_mov_b32_e32 v144, v69
	v_mov_b32_e32 v145, v65
	s_waitcnt vmcnt(5)
	v_mov_b32_e32 v147, v75
	v_mov_b32_e32 v149, v74
	v_mov_b32_e32 v153, v73
	v_mov_b32_e32 v139, v75
	v_mov_b32_e32 v143, v73
	s_waitcnt vmcnt(4)
	v_mov_b32_e32 v146, v95
	v_mov_b32_e32 v148, v94
	v_mov_b32_e32 v152, v93
	v_mov_b32_e32 v138, v95
	v_mov_b32_e32 v95, v74
	v_mov_b32_e32 v142, v93
	s_bitcmp1_b32 s29, 0
	s_cselect_b32 s10, 0x9000, 0
	v_add_u32_e32 v69, s10, v123
	v_mov_b32_e32 v73, v153
	v_mov_b32_e32 v74, v149
	v_mov_b32_e32 v75, v139
	v_mov_b32_e32 v65, v157
	v_mov_b32_e32 v66, v155
	v_mov_b32_e32 v67, v141
	v_mov_b32_e32 v158, v68
	v_mov_b32_e32 v159, v156
	v_mov_b32_e32 v160, v154
	v_mov_b32_e32 v161, v140
	ds_write_b128 v69, v[72:75] offset:9216
	v_and_b32_e32 v75, 0xffff0000, v64
	v_and_b32_e32 v74, 0xffff0000, v68
	ds_write_b128 v69, v[64:67]
	ds_write_b128 v69, v[158:161] offset:4608
	v_mov_b32_e32 v158, v92
	v_mov_b32_e32 v159, v152
	v_mov_b32_e32 v160, v148
	v_mov_b32_e32 v161, v138
	v_lshlrev_b32_e32 v67, 16, v64
	v_lshlrev_b32_e32 v66, 16, v68
	v_pk_mul_f32 v[74:75], v[74:75], v[74:75]
	ds_write_b128 v69, v[158:161] offset:13824
	s_waitcnt vmcnt(3)
	ds_write_b128 v69, v[76:79] offset:18432
	s_waitcnt vmcnt(2)
	ds_write_b128 v69, v[88:91] offset:23040
	s_waitcnt vmcnt(1)
	ds_write_b128 v69, v[80:83] offset:27648
	s_waitcnt vmcnt(0)
	ds_write_b128 v69, v[84:87] offset:32256
	v_lshlrev_b32_e32 v159, 16, v157
	v_lshlrev_b32_e32 v158, 16, v156
	v_pk_fma_f32 v[66:67], v[66:67], v[66:67], v[74:75]
	v_and_b32_e32 v157, 0xffff0000, v157
	v_and_b32_e32 v156, 0xffff0000, v156
	v_pk_fma_f32 v[66:67], v[158:159], v[158:159], v[66:67]
	v_lshlrev_b32_e32 v161, 16, v155
	v_lshlrev_b32_e32 v160, 16, v154
	v_pk_fma_f32 v[66:67], v[156:157], v[156:157], v[66:67]
	v_and_b32_e32 v155, 0xffff0000, v155
	v_and_b32_e32 v154, 0xffff0000, v154
	v_pk_fma_f32 v[66:67], v[160:161], v[160:161], v[66:67]
	v_lshlrev_b32_e32 v163, 16, v151
	v_lshlrev_b32_e32 v162, 16, v150
	v_pk_fma_f32 v[66:67], v[154:155], v[154:155], v[66:67]
	v_and_b32_e32 v151, 0xffff0000, v151
	v_and_b32_e32 v150, 0xffff0000, v150
	v_pk_fma_f32 v[66:67], v[162:163], v[162:163], v[66:67]
	v_and_b32_e32 v75, 0xffff0000, v72
	v_pk_fma_f32 v[66:67], v[150:151], v[150:151], v[66:67]
	v_and_b32_e32 v74, 0xffff0000, v92
	v_pk_add_f32 v[126:127], v[126:127], v[66:67]
	v_lshlrev_b32_e32 v67, 16, v72
	v_lshlrev_b32_e32 v66, 16, v92
	v_pk_mul_f32 v[74:75], v[74:75], v[74:75]
	v_lshlrev_b32_e32 v151, 16, v153
	v_lshlrev_b32_e32 v150, 16, v152
	v_pk_fma_f32 v[66:67], v[66:67], v[66:67], v[74:75]
	v_and_b32_e32 v153, 0xffff0000, v153
	v_and_b32_e32 v152, 0xffff0000, v152
	v_pk_fma_f32 v[66:67], v[150:151], v[150:151], v[66:67]
	v_lshlrev_b32_e32 v155, 16, v149
	v_lshlrev_b32_e32 v154, 16, v148
	v_pk_fma_f32 v[66:67], v[152:153], v[152:153], v[66:67]
	v_and_b32_e32 v149, 0xffff0000, v149
	v_and_b32_e32 v148, 0xffff0000, v148
	v_pk_fma_f32 v[66:67], v[154:155], v[154:155], v[66:67]
	v_lshlrev_b32_e32 v157, 16, v147
	v_lshlrev_b32_e32 v156, 16, v146
	v_pk_fma_f32 v[66:67], v[148:149], v[148:149], v[66:67]
	v_and_b32_e32 v147, 0xffff0000, v147
	v_and_b32_e32 v146, 0xffff0000, v146
	v_pk_fma_f32 v[66:67], v[156:157], v[156:157], v[66:67]
	s_nop 0
	v_pk_fma_f32 v[66:67], v[146:147], v[146:147], v[66:67]
	s_nop 0
	v_pk_add_f32 v[124:125], v[124:125], v[66:67]
